# re-measure: P5 batched epilogue + P5 odd-WG delay only
# speedup vs baseline: 1.0029x; 1.0029x over previous
; template <class Epi, class Sched, bool ALIGN_EPI = false, bool SP2 = false>
; __device__ __forceinline__ void gemm_phase(PG8_LAS unsigned char* lds, const Gemm g, const Sched& S, const Epi& E) {
;     int tid_ = threadIdx.x; asm volatile("" : "+v"(tid_)); const int tid = tid_, wid = __builtin_amdgcn_readfirstlane(tid >> 6), lane = tid & 63, wr = wid >> 2, wc = wid & 3, fr = lane & 15, fq = lane >> 4;
;     const int K = g.K, nt = K / BK;
;     unsigned voffA[2], voffB[2];
; #pragma unroll
;     for (int i = 0; i < 2; ++i) { int R, C; stage_rc(tid * 16 + i * 8192, R, C); const int Rb = Epi::PERM ? ((R & ~31) + perm32(R & 31)) : R;
;         voffA[i] = (unsigned)(R * g.lda + C) * 2u; voffB[i] = (unsigned)(Rb * K + C) * 2u; }
;     const size_t kstep = (size_t)(BK * 2);
;     const size_t hstepA = (size_t)HALF * g.lda * 2, hstepB = (size_t)HALF * K * 2;
;     const size_t tstepA = 2 * hstepA, tstepB = 2 * hstepB;
;     const unsigned ldsw = (unsigned)wid * 1024u;
;     const int aoff = lds_byte(wr * 64 + fr, fq * 8), boff = lds_byte(wc * 32 + fr, fq * 8);
;     ...
;     Unit cur, nxt; int ui = 0;
;     if (!S.next(0, cur)) return;
;     f32x4 acc[2][2][4][2];
; #pragma unroll
;     for (int a = 0; a < 2; ++a)
; #pragma unroll
;         for (int b = 0; b < 2; ++b)
; #pragma unroll
;             for (int m = 0; m < 4; ++m)
; #pragma unroll
;                 for (int n = 0; n < 2; ++n) acc[a][b][m][n] = (f32x4){0.f, 0.f, 0.f, 0.f};
;     bf16x8 At[4][2], B0[2][2], B1[2][2];
;     const char* cA = (const char*)g.A + (size_t)cur.pm * tstepA; const char* cB = (const char*)g.Bt + (size_t)cur.pn * tstepB;
;     S.a_ready(cur);
;     if constexpr (SP2) {
;         PG8_STAGE(PG8_SB(0, 0), cB, voffB); PG8_STAGE(PG8_SB(0, 1), cB + hstepB, voffB); PG8_STAGE(PG8_SA(0, 0), cA, voffA); PG8_STAGE(PG8_SA(0, 1), cA + hstepA, voffA);
;         if (wr == 1) PG8_BAR;
;         PG8_WAIT_V(2); PG8_BAR;
;         PG8_STAGE(PG8_SB(1, 0), cB + kstep, voffB); PG8_STAGE(PG8_SA(1, 0), cA + kstep, voffA); PG8_STAGE(PG8_SB(1, 1), cB + hstepB + kstep, voffB);
;         PG8_WAIT_V(6); PG8_BAR;
; __global__ void __launch_bounds__(512, 2) fwd_megakernel(Params p_unused) {
;     ...
;     pg8::StaticOrder S; S.init(MTOK, DM, G, bx);
;     pg8::Gemm g{Y, WOUT, MTOK, DM, DM, DM}; pg8::EpiRes E{p.x, p.out, mod + 4096};
;     pg8::gemm_phase<pg8::EpiRes, pg8::StaticOrder, true, true>(glds, g, S, E);
.LBB0_600:
	s_or_b64 exec, exec, s[6:7]
	s_mov_b64 s[6:7], s[86:87]
	s_waitcnt lgkmcnt(0)
	v_mov_b32_e32 v0, v194
	v_mov_b32_e32 v8, v194
	s_barrier
	s_bitcmp1_b32 s96, 0
	s_cbranch_scc0 .Lskew_p5_done
	s_sleep 127
	s_sleep 127
	s_sleep 127
.Lskew_p5_done:
	s_and_b64 vcc, exec, s[4:5]
	v_readfirstlane_b32 s5, v8
	s_cbranch_vccnz .LBB0_620
	v_lshlrev_b32_e32 v0, 4, v8
	v_add_u32_e32 v1, 0x2000, v0
	v_ashrrev_i32_e32 v2, 31, v1
	v_lshrrev_b32_e32 v2, 22, v2
	v_add_u32_e32 v2, v1, v2
	v_ashrrev_i32_e32 v9, 10, v2
	v_mul_i32_i24_e32 v3, 0x400, v9
	v_sub_u32_e32 v1, v1, v3
	s_load_dwordx4 s[8:11], s[6:7], 0xc0
	v_lshrrev_b32_e32 v3, 4, v1
	v_bitop3_b32 v1, v3, v1, 32 bitop3:0x6c
	v_ashrrev_i32_e32 v3, 31, v1
	v_lshrrev_b32_e32 v3, 26, v3
	v_add_u32_e32 v3, v1, v3
	s_waitcnt lgkmcnt(0)
	s_add_u32 s0, s10, 0x15c00000
	v_ashrrev_i32_e32 v10, 6, v3
	v_and_b32_e32 v3, 0xc0, v3
	s_addc_u32 s1, s11, 0
	v_sub_u32_e32 v1, v1, v3
	v_mov_b32_e32 v3, 1
	s_add_u32 s2, s10, 0x7c00000
	v_lshlrev_b32_e32 v2, 5, v9
	v_ashrrev_i16_sdwa v1, v3, sext(v1) dst_sel:DWORD dst_unused:UNUSED_PAD src0_sel:DWORD src1_sel:BYTE_0
	s_addc_u32 s3, s11, 0
	s_ashr_i32 s19, s5, 6
	v_and_b32_e32 v2, 32, v2
	v_bfe_i32 v11, v1, 0, 16
	s_ashr_i32 s18, s5, 8
	s_lshl_b32 s33, s19, 10
	v_add_u32_e32 v1, v2, v11
	v_lshlrev_b32_e32 v2, 3, v9
	v_and_b32_e32 v2, 0xffff0, v2
	s_and_b64 s[16:17], s[12:13], exec
	v_add_lshl_u32 v2, v10, v2, 12
	s_cselect_b32 s4, s59, s58
	v_lshl_add_u32 v144, v1, 1, v2
	v_bfe_i32 v2, v8, 27, 1
	s_add_i32 s4, s4, s57
	v_lshrrev_b32_e32 v2, 22, v2
	s_ashr_i32 s16, s4, 31
	v_add_u32_e32 v2, v0, v2
	s_lshr_b32 s16, s16, 27
	v_and_b32_e32 v2, 0xfffffc00, v2
	s_add_i32 s16, s4, s16
	v_sub_u32_e32 v0, v0, v2
	s_ashr_i32 s17, s16, 5
	s_and_b32 s16, s16, 0xffe0
	v_lshrrev_b32_e32 v2, 4, v0
	s_sub_i32 s16, s4, s16
	v_bitop3_b32 v0, v2, v0, 32 bitop3:0x6c
	s_bfe_i32 s4, s16, 0x80000
	v_ashrrev_i32_e32 v2, 31, v0
	s_bfe_u32 s4, s4, 0x2000d
	v_ashrrev_i32_e32 v1, 31, v8
	v_lshrrev_b32_e32 v2, 26, v2
	s_add_i32 s20, s16, s4
	v_lshrrev_b32_e32 v1, 26, v1
	v_add_u32_e32 v2, v0, v2
	s_bfe_i32 s4, s20, 0x80000
	s_and_b32 s20, s20, 0xfc
	v_add_u32_e32 v1, v8, v1
	v_ashrrev_i32_e32 v13, 6, v2
	v_and_b32_e32 v2, 0xc0, v2
	s_sub_i32 s16, s16, s20
	v_ashrrev_i32_e32 v12, 6, v1
	v_sub_u32_e32 v0, v0, v2
	s_lshl_b32 s17, s17, 2
	s_sext_i32_i16 s4, s4
	s_sext_i32_i8 s16, s16
	v_lshlrev_b32_e32 v1, 5, v12
	v_ashrrev_i16_sdwa v0, v3, sext(v0) dst_sel:DWORD dst_unused:UNUSED_PAD src0_sel:DWORD src1_sel:BYTE_0
	s_lshr_b32 s4, s4, 2
	s_add_i32 s38, s17, s16
	v_and_b32_e32 v1, 32, v1
	v_bfe_i32 v14, v0, 0, 16
	s_ashr_i32 s39, s38, 31
	s_bfe_i64 s[20:21], s[4:5], 0x100000
	v_add_u32_e32 v0, v1, v14
	v_lshlrev_b32_e32 v1, 3, v12
	s_lshl_b64 s[16:17], s[38:39], 20
	s_lshl_b64 s[20:21], s[20:21], 20
	v_and_b32_e32 v1, 0xffff0, v1
	s_add_u32 s42, s2, s20
	v_add_lshl_u32 v1, v13, v1, 12
	s_addc_u32 s43, s3, s21
	s_add_i32 s39, s33, 0
	v_lshl_add_u32 v146, v0, 1, v1
	s_add_i32 m0, s39, 0x10000
	s_load_dwordx2 s[6:7], s[6:7], 0x0
	global_load_lds_dwordx4 v146, s[42:43]
	s_add_i32 m0, s39, 0x12000
	s_add_u32 s20, s42, 0x80000
	global_load_lds_dwordx4 v144, s[42:43]
	s_addc_u32 s21, s43, 0
	s_add_i32 m0, s39, 0x14000
	v_mov_b32_e32 v147, 0
	global_load_lds_dwordx4 v146, s[20:21]
	s_add_i32 m0, s39, 0x16000
	s_add_u32 s40, s0, s16
	s_addc_u32 s41, s1, s17
	s_add_i32 s46, s39, 0x2000
	global_load_lds_dwordx4 v144, s[20:21]
	s_mov_b32 m0, s39
	s_add_u32 s16, s40, 0x80000
	global_load_lds_dwordx4 v146, s[40:41]
	s_mov_b32 m0, s46
	s_addc_u32 s17, s41, 0
	s_add_i32 s47, s39, 0x4000
	global_load_lds_dwordx4 v144, s[40:41]
	s_mov_b32 m0, s47
	s_add_i32 s48, s39, 0x6000
	global_load_lds_dwordx4 v146, s[16:17]
	s_mov_b32 m0, s48
	v_mov_b32_e32 v145, v147
	global_load_lds_dwordx4 v144, s[16:17]
	s_cmp_eq_u32 s18, 1
	s_mov_b32 s49, 0
	v_lshl_add_u64 v[6:7], s[42:43], 0, v[146:147]
	v_lshl_add_u64 v[4:5], s[42:43], 0, v[144:145]
	v_lshl_add_u64 v[0:1], s[40:41], 0, v[146:147]
	s_cselect_b64 s[16:17], -1, 0
	s_cmp_lg_u32 s18, 1
	v_lshl_add_u64 v[2:3], s[40:41], 0, v[144:145]
	s_cbranch_scc1 .LBB0_603
	s_barrier
